# same as previous + restore of the kernel-wide constant register v239 at the end of the hand-written out-proj epilogue (robustness)
# speedup vs baseline: 1.0415x; 1.0008x over previous
.Lo4_n_out:
	ds_read_b32 v194, v217 offset:4096
	ds_read_b32 v195, v217 offset:4160
	ds_read_b32 v196, v217 offset:4224
	ds_read_b32 v197, v217 offset:4288
	ds_read_b32 v198, v217 offset:4608
	ds_read_b32 v199, v217 offset:4672
	ds_read_b32 v200, v217 offset:4736
	ds_read_b32 v201, v217 offset:4800
	s_waitcnt lgkmcnt(0)
	v_pk_mul_f32 v[236:237], v[126:127], v[194:195] op_sel_hi:[1,0]
	v_pk_mul_f32 v[236:237], v[146:147], v[236:237]
	v_pk_add_f32 v[236:237], v[178:179], v[236:237]
	v_cvt_pk_bf16_f32 v202, v236, v237
	v_pk_mul_f32 v[236:237], v[128:129], v[194:195] op_sel_hi:[1,0]
	v_pk_mul_f32 v[236:237], v[148:149], v[236:237]
	v_pk_add_f32 v[236:237], v[180:181], v[236:237]
	v_cvt_pk_bf16_f32 v203, v236, v237
	v_pk_mul_f32 v[236:237], v[122:123], v[194:195] op_sel_hi:[1,0]
	v_pk_fma_f32 v[236:237], v[150:151], v[236:237], v[182:183]
	v_cvt_pk_bf16_f32 v204, v236, v237
	v_pk_mul_f32 v[236:237], v[124:125], v[194:195] op_sel_hi:[1,0]
	v_pk_fma_f32 v[236:237], v[152:153], v[236:237], v[184:185]
	v_cvt_pk_bf16_f32 v205, v236, v237
	global_store_dwordx4 v213, v[202:205], s[8:9] sc1
	v_pk_mul_f32 v[236:237], v[118:119], v[194:195] op_sel_hi:[1,0]
	v_pk_mul_f32 v[236:237], v[154:155], v[236:237]
	v_pk_add_f32 v[236:237], v[186:187], v[236:237]
	v_cvt_pk_bf16_f32 v206, v236, v237
	v_pk_mul_f32 v[236:237], v[120:121], v[194:195] op_sel_hi:[1,0]
	v_pk_mul_f32 v[236:237], v[156:157], v[236:237]
	v_pk_add_f32 v[236:237], v[188:189], v[236:237]
	v_cvt_pk_bf16_f32 v207, v236, v237
	v_pk_mul_f32 v[236:237], v[114:115], v[194:195] op_sel_hi:[1,0]
	v_pk_fma_f32 v[236:237], v[158:159], v[236:237], v[190:191]
	v_cvt_pk_bf16_f32 v208, v236, v237
	v_pk_mul_f32 v[236:237], v[116:117], v[194:195] op_sel_hi:[1,0]
	v_pk_fma_f32 v[236:237], v[160:161], v[236:237], v[192:193]
	v_cvt_pk_bf16_f32 v209, v236, v237
	global_store_dwordx4 v213, v[206:209], s[8:9] offset:256 sc1
	s_add_u32 s8, s8, 0x8000
	s_addc_u32 s9, s9, 0
	v_pk_mul_f32 v[236:237], v[108:109], v[194:195] op_sel:[0,1] op_sel_hi:[1,1]
	v_pk_mul_f32 v[236:237], v[146:147], v[236:237]
	v_pk_add_f32 v[236:237], v[178:179], v[236:237]
	v_cvt_pk_bf16_f32 v202, v236, v237
	v_pk_mul_f32 v[236:237], v[110:111], v[194:195] op_sel:[0,1] op_sel_hi:[1,1]
	v_pk_mul_f32 v[236:237], v[148:149], v[236:237]
	v_pk_add_f32 v[236:237], v[180:181], v[236:237]
	v_cvt_pk_bf16_f32 v203, v236, v237
	v_pk_mul_f32 v[236:237], v[104:105], v[194:195] op_sel:[0,1] op_sel_hi:[1,1]
	v_pk_fma_f32 v[236:237], v[150:151], v[236:237], v[182:183]
	v_cvt_pk_bf16_f32 v204, v236, v237
	v_pk_mul_f32 v[236:237], v[106:107], v[194:195] op_sel:[0,1] op_sel_hi:[1,1]
	v_pk_fma_f32 v[236:237], v[152:153], v[236:237], v[184:185]
	v_cvt_pk_bf16_f32 v205, v236, v237
	global_store_dwordx4 v213, v[202:205], s[8:9] sc1
	v_pk_mul_f32 v[236:237], v[100:101], v[194:195] op_sel:[0,1] op_sel_hi:[1,1]
	v_pk_mul_f32 v[236:237], v[154:155], v[236:237]
	v_pk_add_f32 v[236:237], v[186:187], v[236:237]
	v_cvt_pk_bf16_f32 v206, v236, v237
	v_pk_mul_f32 v[236:237], v[102:103], v[194:195] op_sel:[0,1] op_sel_hi:[1,1]
	v_pk_mul_f32 v[236:237], v[156:157], v[236:237]
	v_pk_add_f32 v[236:237], v[188:189], v[236:237]
	v_cvt_pk_bf16_f32 v207, v236, v237
	v_pk_mul_f32 v[236:237], v[96:97], v[194:195] op_sel:[0,1] op_sel_hi:[1,1]
	v_pk_fma_f32 v[236:237], v[158:159], v[236:237], v[190:191]
	v_cvt_pk_bf16_f32 v208, v236, v237
	v_pk_mul_f32 v[236:237], v[98:99], v[194:195] op_sel:[0,1] op_sel_hi:[1,1]
	v_pk_fma_f32 v[236:237], v[160:161], v[236:237], v[192:193]
	v_cvt_pk_bf16_f32 v209, v236, v237
	global_store_dwordx4 v213, v[206:209], s[8:9] offset:256 sc1
	s_add_u32 s8, s8, 0x8000
	s_addc_u32 s9, s9, 0
	v_pk_mul_f32 v[236:237], v[92:93], v[196:197] op_sel_hi:[1,0]
	v_pk_mul_f32 v[236:237], v[146:147], v[236:237]
	v_pk_add_f32 v[236:237], v[178:179], v[236:237]
	v_cvt_pk_bf16_f32 v202, v236, v237
	v_pk_mul_f32 v[236:237], v[94:95], v[196:197] op_sel_hi:[1,0]
	v_pk_mul_f32 v[236:237], v[148:149], v[236:237]
	v_pk_add_f32 v[236:237], v[180:181], v[236:237]
	v_cvt_pk_bf16_f32 v203, v236, v237
	v_pk_mul_f32 v[236:237], v[88:89], v[196:197] op_sel_hi:[1,0]
	v_pk_fma_f32 v[236:237], v[150:151], v[236:237], v[182:183]
	v_cvt_pk_bf16_f32 v204, v236, v237
	v_pk_mul_f32 v[236:237], v[90:91], v[196:197] op_sel_hi:[1,0]
	v_pk_fma_f32 v[236:237], v[152:153], v[236:237], v[184:185]
	v_cvt_pk_bf16_f32 v205, v236, v237
	global_store_dwordx4 v213, v[202:205], s[8:9] sc1
	v_pk_mul_f32 v[236:237], v[84:85], v[196:197] op_sel_hi:[1,0]
	v_pk_mul_f32 v[236:237], v[154:155], v[236:237]
	v_pk_add_f32 v[236:237], v[186:187], v[236:237]
	v_cvt_pk_bf16_f32 v206, v236, v237
	v_pk_mul_f32 v[236:237], v[86:87], v[196:197] op_sel_hi:[1,0]
	v_pk_mul_f32 v[236:237], v[156:157], v[236:237]
	v_pk_add_f32 v[236:237], v[188:189], v[236:237]
	v_cvt_pk_bf16_f32 v207, v236, v237
	v_pk_mul_f32 v[236:237], v[80:81], v[196:197] op_sel_hi:[1,0]
	v_pk_fma_f32 v[236:237], v[158:159], v[236:237], v[190:191]
	v_cvt_pk_bf16_f32 v208, v236, v237
	v_pk_mul_f32 v[236:237], v[82:83], v[196:197] op_sel_hi:[1,0]
	v_pk_fma_f32 v[236:237], v[160:161], v[236:237], v[192:193]
	v_cvt_pk_bf16_f32 v209, v236, v237
	global_store_dwordx4 v213, v[206:209], s[8:9] offset:256 sc1
	s_add_u32 s8, s8, 0x8000
	s_addc_u32 s9, s9, 0
	v_pk_mul_f32 v[236:237], v[76:77], v[196:197] op_sel:[0,1] op_sel_hi:[1,1]
	v_pk_mul_f32 v[236:237], v[146:147], v[236:237]
	v_pk_add_f32 v[236:237], v[178:179], v[236:237]
	v_cvt_pk_bf16_f32 v202, v236, v237
	v_pk_mul_f32 v[236:237], v[78:79], v[196:197] op_sel:[0,1] op_sel_hi:[1,1]
	v_pk_mul_f32 v[236:237], v[148:149], v[236:237]
	v_pk_add_f32 v[236:237], v[180:181], v[236:237]
	v_cvt_pk_bf16_f32 v203, v236, v237
	v_pk_mul_f32 v[236:237], v[72:73], v[196:197] op_sel:[0,1] op_sel_hi:[1,1]
	v_pk_fma_f32 v[236:237], v[150:151], v[236:237], v[182:183]
	v_cvt_pk_bf16_f32 v204, v236, v237
	v_pk_mul_f32 v[236:237], v[74:75], v[196:197] op_sel:[0,1] op_sel_hi:[1,1]
	v_pk_fma_f32 v[236:237], v[152:153], v[236:237], v[184:185]
	v_cvt_pk_bf16_f32 v205, v236, v237
	global_store_dwordx4 v213, v[202:205], s[8:9] sc1
	v_pk_mul_f32 v[236:237], v[68:69], v[196:197] op_sel:[0,1] op_sel_hi:[1,1]
	v_pk_mul_f32 v[236:237], v[154:155], v[236:237]
	v_pk_add_f32 v[236:237], v[186:187], v[236:237]
	v_cvt_pk_bf16_f32 v206, v236, v237
	v_pk_mul_f32 v[236:237], v[70:71], v[196:197] op_sel:[0,1] op_sel_hi:[1,1]
	v_pk_mul_f32 v[236:237], v[156:157], v[236:237]
	v_pk_add_f32 v[236:237], v[188:189], v[236:237]
	v_cvt_pk_bf16_f32 v207, v236, v237
	v_pk_mul_f32 v[236:237], v[64:65], v[196:197] op_sel:[0,1] op_sel_hi:[1,1]
	v_pk_fma_f32 v[236:237], v[158:159], v[236:237], v[190:191]
	v_cvt_pk_bf16_f32 v208, v236, v237
	v_pk_mul_f32 v[236:237], v[66:67], v[196:197] op_sel:[0,1] op_sel_hi:[1,1]
	v_pk_fma_f32 v[236:237], v[160:161], v[236:237], v[192:193]
	v_cvt_pk_bf16_f32 v209, v236, v237
	global_store_dwordx4 v213, v[206:209], s[8:9] offset:256 sc1
	s_add_u32 s8, s8, 0x28000
	s_addc_u32 s9, s9, 0
	v_pk_mul_f32 v[236:237], v[60:61], v[198:199] op_sel_hi:[1,0]
	v_pk_mul_f32 v[236:237], v[146:147], v[236:237]
	v_pk_add_f32 v[236:237], v[178:179], v[236:237]
	v_cvt_pk_bf16_f32 v202, v236, v237
	v_pk_mul_f32 v[236:237], v[62:63], v[198:199] op_sel_hi:[1,0]
	v_pk_mul_f32 v[236:237], v[148:149], v[236:237]
	v_pk_add_f32 v[236:237], v[180:181], v[236:237]
	v_cvt_pk_bf16_f32 v203, v236, v237
	v_pk_mul_f32 v[236:237], v[56:57], v[198:199] op_sel_hi:[1,0]
	v_pk_fma_f32 v[236:237], v[150:151], v[236:237], v[182:183]
	v_cvt_pk_bf16_f32 v204, v236, v237
	v_pk_mul_f32 v[236:237], v[58:59], v[198:199] op_sel_hi:[1,0]
	v_pk_fma_f32 v[236:237], v[152:153], v[236:237], v[184:185]
	v_cvt_pk_bf16_f32 v205, v236, v237
	global_store_dwordx4 v213, v[202:205], s[8:9] sc1
	v_pk_mul_f32 v[236:237], v[52:53], v[198:199] op_sel_hi:[1,0]
	v_pk_mul_f32 v[236:237], v[154:155], v[236:237]
	v_pk_add_f32 v[236:237], v[186:187], v[236:237]
	v_cvt_pk_bf16_f32 v206, v236, v237
	v_pk_mul_f32 v[236:237], v[54:55], v[198:199] op_sel_hi:[1,0]
	v_pk_mul_f32 v[236:237], v[156:157], v[236:237]
	v_pk_add_f32 v[236:237], v[188:189], v[236:237]
	v_cvt_pk_bf16_f32 v207, v236, v237
	v_pk_mul_f32 v[236:237], v[48:49], v[198:199] op_sel_hi:[1,0]
	v_pk_fma_f32 v[236:237], v[158:159], v[236:237], v[190:191]
	v_cvt_pk_bf16_f32 v208, v236, v237
	v_pk_mul_f32 v[236:237], v[50:51], v[198:199] op_sel_hi:[1,0]
	v_pk_fma_f32 v[236:237], v[160:161], v[236:237], v[192:193]
	v_cvt_pk_bf16_f32 v209, v236, v237
	global_store_dwordx4 v213, v[206:209], s[8:9] offset:256 sc1
	s_add_u32 s8, s8, 0x8000
	s_addc_u32 s9, s9, 0
	v_pk_mul_f32 v[236:237], v[44:45], v[198:199] op_sel:[0,1] op_sel_hi:[1,1]
	v_pk_mul_f32 v[236:237], v[146:147], v[236:237]
	v_pk_add_f32 v[236:237], v[178:179], v[236:237]
	v_cvt_pk_bf16_f32 v202, v236, v237
	v_pk_mul_f32 v[236:237], v[46:47], v[198:199] op_sel:[0,1] op_sel_hi:[1,1]
	v_pk_mul_f32 v[236:237], v[148:149], v[236:237]
	v_pk_add_f32 v[236:237], v[180:181], v[236:237]
	v_cvt_pk_bf16_f32 v203, v236, v237
	v_pk_mul_f32 v[236:237], v[40:41], v[198:199] op_sel:[0,1] op_sel_hi:[1,1]
	v_pk_fma_f32 v[236:237], v[150:151], v[236:237], v[182:183]
	v_cvt_pk_bf16_f32 v204, v236, v237
	v_pk_mul_f32 v[236:237], v[42:43], v[198:199] op_sel:[0,1] op_sel_hi:[1,1]
	v_pk_fma_f32 v[236:237], v[152:153], v[236:237], v[184:185]
	v_cvt_pk_bf16_f32 v205, v236, v237
	global_store_dwordx4 v213, v[202:205], s[8:9] sc1
	v_pk_mul_f32 v[236:237], v[36:37], v[198:199] op_sel:[0,1] op_sel_hi:[1,1]
	v_pk_mul_f32 v[236:237], v[154:155], v[236:237]
	v_pk_add_f32 v[236:237], v[186:187], v[236:237]
	v_cvt_pk_bf16_f32 v206, v236, v237
	v_pk_mul_f32 v[236:237], v[38:39], v[198:199] op_sel:[0,1] op_sel_hi:[1,1]
	v_pk_mul_f32 v[236:237], v[156:157], v[236:237]
	v_pk_add_f32 v[236:237], v[188:189], v[236:237]
	v_cvt_pk_bf16_f32 v207, v236, v237
	v_pk_mul_f32 v[236:237], v[32:33], v[198:199] op_sel:[0,1] op_sel_hi:[1,1]
	v_pk_fma_f32 v[236:237], v[158:159], v[236:237], v[190:191]
	v_cvt_pk_bf16_f32 v208, v236, v237
	v_pk_mul_f32 v[236:237], v[34:35], v[198:199] op_sel:[0,1] op_sel_hi:[1,1]
	v_pk_fma_f32 v[236:237], v[160:161], v[236:237], v[192:193]
	v_cvt_pk_bf16_f32 v209, v236, v237
	global_store_dwordx4 v213, v[206:209], s[8:9] offset:256 sc1
	s_add_u32 s8, s8, 0x8000
	s_addc_u32 s9, s9, 0
	v_pk_mul_f32 v[236:237], v[28:29], v[200:201] op_sel_hi:[1,0]
	v_pk_mul_f32 v[236:237], v[146:147], v[236:237]
	v_pk_add_f32 v[236:237], v[178:179], v[236:237]
	v_cvt_pk_bf16_f32 v202, v236, v237
	v_pk_mul_f32 v[236:237], v[30:31], v[200:201] op_sel_hi:[1,0]
	v_pk_mul_f32 v[236:237], v[148:149], v[236:237]
	v_pk_add_f32 v[236:237], v[180:181], v[236:237]
	v_cvt_pk_bf16_f32 v203, v236, v237
	v_pk_mul_f32 v[236:237], v[24:25], v[200:201] op_sel_hi:[1,0]
	v_pk_fma_f32 v[236:237], v[150:151], v[236:237], v[182:183]
	v_cvt_pk_bf16_f32 v204, v236, v237
	v_pk_mul_f32 v[236:237], v[26:27], v[200:201] op_sel_hi:[1,0]
	v_pk_fma_f32 v[236:237], v[152:153], v[236:237], v[184:185]
	v_cvt_pk_bf16_f32 v205, v236, v237
	global_store_dwordx4 v213, v[202:205], s[8:9] sc1
	v_pk_mul_f32 v[236:237], v[20:21], v[200:201] op_sel_hi:[1,0]
	v_pk_mul_f32 v[236:237], v[154:155], v[236:237]
	v_pk_add_f32 v[236:237], v[186:187], v[236:237]
	v_cvt_pk_bf16_f32 v206, v236, v237
	v_pk_mul_f32 v[236:237], v[22:23], v[200:201] op_sel_hi:[1,0]
	v_pk_mul_f32 v[236:237], v[156:157], v[236:237]
	v_pk_add_f32 v[236:237], v[188:189], v[236:237]
	v_cvt_pk_bf16_f32 v207, v236, v237
	v_pk_mul_f32 v[236:237], v[16:17], v[200:201] op_sel_hi:[1,0]
	v_pk_fma_f32 v[236:237], v[158:159], v[236:237], v[190:191]
	v_cvt_pk_bf16_f32 v208, v236, v237
	v_pk_mul_f32 v[236:237], v[18:19], v[200:201] op_sel_hi:[1,0]
	v_pk_fma_f32 v[236:237], v[160:161], v[236:237], v[192:193]
	v_cvt_pk_bf16_f32 v209, v236, v237
	global_store_dwordx4 v213, v[206:209], s[8:9] offset:256 sc1
	s_add_u32 s8, s8, 0x8000
	s_addc_u32 s9, s9, 0
	v_pk_mul_f32 v[236:237], v[12:13], v[200:201] op_sel:[0,1] op_sel_hi:[1,1]
	v_pk_mul_f32 v[236:237], v[146:147], v[236:237]
	v_pk_add_f32 v[236:237], v[178:179], v[236:237]
	v_cvt_pk_bf16_f32 v202, v236, v237
	v_pk_mul_f32 v[236:237], v[14:15], v[200:201] op_sel:[0,1] op_sel_hi:[1,1]
	v_pk_mul_f32 v[236:237], v[148:149], v[236:237]
	v_pk_add_f32 v[236:237], v[180:181], v[236:237]
	v_cvt_pk_bf16_f32 v203, v236, v237
	v_pk_mul_f32 v[236:237], v[4:5], v[200:201] op_sel:[0,1] op_sel_hi:[1,1]
	v_pk_fma_f32 v[236:237], v[150:151], v[236:237], v[182:183]
	v_cvt_pk_bf16_f32 v204, v236, v237
	v_pk_mul_f32 v[236:237], v[6:7], v[200:201] op_sel:[0,1] op_sel_hi:[1,1]
	v_pk_fma_f32 v[236:237], v[152:153], v[236:237], v[184:185]
	v_cvt_pk_bf16_f32 v205, v236, v237
	global_store_dwordx4 v213, v[202:205], s[8:9] sc1
	v_pk_mul_f32 v[236:237], v[8:9], v[200:201] op_sel:[0,1] op_sel_hi:[1,1]
	v_pk_mul_f32 v[236:237], v[154:155], v[236:237]
	v_pk_add_f32 v[236:237], v[186:187], v[236:237]
	v_cvt_pk_bf16_f32 v206, v236, v237
	v_pk_mul_f32 v[236:237], v[10:11], v[200:201] op_sel:[0,1] op_sel_hi:[1,1]
	v_pk_mul_f32 v[236:237], v[156:157], v[236:237]
	v_pk_add_f32 v[236:237], v[188:189], v[236:237]
	v_cvt_pk_bf16_f32 v207, v236, v237
	v_pk_mul_f32 v[236:237], v[0:1], v[200:201] op_sel:[0,1] op_sel_hi:[1,1]
	v_pk_fma_f32 v[236:237], v[158:159], v[236:237], v[190:191]
	v_cvt_pk_bf16_f32 v208, v236, v237
	v_pk_mul_f32 v[236:237], v[2:3], v[200:201] op_sel:[0,1] op_sel_hi:[1,1]
	v_pk_fma_f32 v[236:237], v[160:161], v[236:237], v[192:193]
	v_cvt_pk_bf16_f32 v209, v236, v237
	global_store_dwordx4 v213, v[206:209], s[8:9] offset:256 sc1
	s_waitcnt vmcnt(0)
	s_mov_b64 exec, 1
	global_atomic_add v113, v246, s[26:27]
	s_mov_b64 exec, -1
	v_mov_b32_e32 v239, 0x120000
	s_branch .LBB0_1145

.Lo4_l_out:
	ds_read_b32 v194, v217 offset:4096
	ds_read_b32 v195, v217 offset:4160
	ds_read_b32 v196, v217 offset:4224
	ds_read_b32 v197, v217 offset:4288
	ds_read_b32 v198, v217 offset:4608
	ds_read_b32 v199, v217 offset:4672
	ds_read_b32 v200, v217 offset:4736
	ds_read_b32 v201, v217 offset:4800
	s_waitcnt lgkmcnt(0)
	v_pk_mul_f32 v[236:237], v[126:127], v[194:195] op_sel_hi:[1,0]
	v_pk_mul_f32 v[202:203], v[146:147], v[236:237]
	v_pk_mul_f32 v[236:237], v[128:129], v[194:195] op_sel_hi:[1,0]
	v_pk_mul_f32 v[204:205], v[148:149], v[236:237]
	global_store_dwordx4 v211, v[202:205], s[8:9] offset:0
	v_pk_mul_f32 v[236:237], v[122:123], v[194:195] op_sel_hi:[1,0]
	v_pk_mul_f32 v[206:207], v[150:151], v[236:237]
	v_pk_mul_f32 v[236:237], v[124:125], v[194:195] op_sel_hi:[1,0]
	v_pk_mul_f32 v[208:209], v[152:153], v[236:237]
	global_store_dwordx4 v211, v[206:209], s[8:9] offset:16
	v_pk_mul_f32 v[236:237], v[118:119], v[194:195] op_sel_hi:[1,0]
	v_pk_mul_f32 v[202:203], v[154:155], v[236:237]
	v_pk_mul_f32 v[236:237], v[120:121], v[194:195] op_sel_hi:[1,0]
	v_pk_mul_f32 v[204:205], v[156:157], v[236:237]
	global_store_dwordx4 v211, v[202:205], s[8:9] offset:512
	v_pk_mul_f32 v[236:237], v[114:115], v[194:195] op_sel_hi:[1,0]
	v_pk_mul_f32 v[206:207], v[158:159], v[236:237]
	v_pk_mul_f32 v[236:237], v[116:117], v[194:195] op_sel_hi:[1,0]
	v_pk_mul_f32 v[208:209], v[160:161], v[236:237]
	global_store_dwordx4 v211, v[206:209], s[8:9] offset:528
	s_add_u32 s8, s8, 0x10000
	s_addc_u32 s9, s9, 0
	v_pk_mul_f32 v[236:237], v[108:109], v[194:195] op_sel:[0,1] op_sel_hi:[1,1]
	v_pk_mul_f32 v[202:203], v[146:147], v[236:237]
	v_pk_mul_f32 v[236:237], v[110:111], v[194:195] op_sel:[0,1] op_sel_hi:[1,1]
	v_pk_mul_f32 v[204:205], v[148:149], v[236:237]
	global_store_dwordx4 v211, v[202:205], s[8:9] offset:0
	v_pk_mul_f32 v[236:237], v[104:105], v[194:195] op_sel:[0,1] op_sel_hi:[1,1]
	v_pk_mul_f32 v[206:207], v[150:151], v[236:237]
	v_pk_mul_f32 v[236:237], v[106:107], v[194:195] op_sel:[0,1] op_sel_hi:[1,1]
	v_pk_mul_f32 v[208:209], v[152:153], v[236:237]
	global_store_dwordx4 v211, v[206:209], s[8:9] offset:16
	v_pk_mul_f32 v[236:237], v[100:101], v[194:195] op_sel:[0,1] op_sel_hi:[1,1]
	v_pk_mul_f32 v[202:203], v[154:155], v[236:237]
	v_pk_mul_f32 v[236:237], v[102:103], v[194:195] op_sel:[0,1] op_sel_hi:[1,1]
	v_pk_mul_f32 v[204:205], v[156:157], v[236:237]
	global_store_dwordx4 v211, v[202:205], s[8:9] offset:512
	v_pk_mul_f32 v[236:237], v[96:97], v[194:195] op_sel:[0,1] op_sel_hi:[1,1]
	v_pk_mul_f32 v[206:207], v[158:159], v[236:237]
	v_pk_mul_f32 v[236:237], v[98:99], v[194:195] op_sel:[0,1] op_sel_hi:[1,1]
	v_pk_mul_f32 v[208:209], v[160:161], v[236:237]
	global_store_dwordx4 v211, v[206:209], s[8:9] offset:528
	s_add_u32 s8, s8, 0x10000
	s_addc_u32 s9, s9, 0
	v_pk_mul_f32 v[236:237], v[92:93], v[196:197] op_sel_hi:[1,0]
	v_pk_mul_f32 v[202:203], v[146:147], v[236:237]
	v_pk_mul_f32 v[236:237], v[94:95], v[196:197] op_sel_hi:[1,0]
	v_pk_mul_f32 v[204:205], v[148:149], v[236:237]
	global_store_dwordx4 v211, v[202:205], s[8:9] offset:0
	v_pk_mul_f32 v[236:237], v[88:89], v[196:197] op_sel_hi:[1,0]
	v_pk_mul_f32 v[206:207], v[150:151], v[236:237]
	v_pk_mul_f32 v[236:237], v[90:91], v[196:197] op_sel_hi:[1,0]
	v_pk_mul_f32 v[208:209], v[152:153], v[236:237]
	global_store_dwordx4 v211, v[206:209], s[8:9] offset:16
	v_pk_mul_f32 v[236:237], v[84:85], v[196:197] op_sel_hi:[1,0]
	v_pk_mul_f32 v[202:203], v[154:155], v[236:237]
	v_pk_mul_f32 v[236:237], v[86:87], v[196:197] op_sel_hi:[1,0]
	v_pk_mul_f32 v[204:205], v[156:157], v[236:237]
	global_store_dwordx4 v211, v[202:205], s[8:9] offset:512
	v_pk_mul_f32 v[236:237], v[80:81], v[196:197] op_sel_hi:[1,0]
	v_pk_mul_f32 v[206:207], v[158:159], v[236:237]
	v_pk_mul_f32 v[236:237], v[82:83], v[196:197] op_sel_hi:[1,0]
	v_pk_mul_f32 v[208:209], v[160:161], v[236:237]
	global_store_dwordx4 v211, v[206:209], s[8:9] offset:528
	s_add_u32 s8, s8, 0x10000
	s_addc_u32 s9, s9, 0
	v_pk_mul_f32 v[236:237], v[76:77], v[196:197] op_sel:[0,1] op_sel_hi:[1,1]
	v_pk_mul_f32 v[202:203], v[146:147], v[236:237]
	v_pk_mul_f32 v[236:237], v[78:79], v[196:197] op_sel:[0,1] op_sel_hi:[1,1]
	v_pk_mul_f32 v[204:205], v[148:149], v[236:237]
	global_store_dwordx4 v211, v[202:205], s[8:9] offset:0
	v_pk_mul_f32 v[236:237], v[72:73], v[196:197] op_sel:[0,1] op_sel_hi:[1,1]
	v_pk_mul_f32 v[206:207], v[150:151], v[236:237]
	v_pk_mul_f32 v[236:237], v[74:75], v[196:197] op_sel:[0,1] op_sel_hi:[1,1]
	v_pk_mul_f32 v[208:209], v[152:153], v[236:237]
	global_store_dwordx4 v211, v[206:209], s[8:9] offset:16
	v_pk_mul_f32 v[236:237], v[68:69], v[196:197] op_sel:[0,1] op_sel_hi:[1,1]
	v_pk_mul_f32 v[202:203], v[154:155], v[236:237]
	v_pk_mul_f32 v[236:237], v[70:71], v[196:197] op_sel:[0,1] op_sel_hi:[1,1]
	v_pk_mul_f32 v[204:205], v[156:157], v[236:237]
	global_store_dwordx4 v211, v[202:205], s[8:9] offset:512
	v_pk_mul_f32 v[236:237], v[64:65], v[196:197] op_sel:[0,1] op_sel_hi:[1,1]
	v_pk_mul_f32 v[206:207], v[158:159], v[236:237]
	v_pk_mul_f32 v[236:237], v[66:67], v[196:197] op_sel:[0,1] op_sel_hi:[1,1]
	v_pk_mul_f32 v[208:209], v[160:161], v[236:237]
	global_store_dwordx4 v211, v[206:209], s[8:9] offset:528
	s_add_u32 s8, s8, 0x50000
	s_addc_u32 s9, s9, 0
	v_pk_mul_f32 v[236:237], v[60:61], v[198:199] op_sel_hi:[1,0]
	v_pk_mul_f32 v[202:203], v[146:147], v[236:237]
	v_pk_mul_f32 v[236:237], v[62:63], v[198:199] op_sel_hi:[1,0]
	v_pk_mul_f32 v[204:205], v[148:149], v[236:237]
	global_store_dwordx4 v211, v[202:205], s[8:9] offset:0
	v_pk_mul_f32 v[236:237], v[56:57], v[198:199] op_sel_hi:[1,0]
	v_pk_mul_f32 v[206:207], v[150:151], v[236:237]
	v_pk_mul_f32 v[236:237], v[58:59], v[198:199] op_sel_hi:[1,0]
	v_pk_mul_f32 v[208:209], v[152:153], v[236:237]
	global_store_dwordx4 v211, v[206:209], s[8:9] offset:16
	v_pk_mul_f32 v[236:237], v[52:53], v[198:199] op_sel_hi:[1,0]
	v_pk_mul_f32 v[202:203], v[154:155], v[236:237]
	v_pk_mul_f32 v[236:237], v[54:55], v[198:199] op_sel_hi:[1,0]
	v_pk_mul_f32 v[204:205], v[156:157], v[236:237]
	global_store_dwordx4 v211, v[202:205], s[8:9] offset:512
	v_pk_mul_f32 v[236:237], v[48:49], v[198:199] op_sel_hi:[1,0]
	v_pk_mul_f32 v[206:207], v[158:159], v[236:237]
	v_pk_mul_f32 v[236:237], v[50:51], v[198:199] op_sel_hi:[1,0]
	v_pk_mul_f32 v[208:209], v[160:161], v[236:237]
	global_store_dwordx4 v211, v[206:209], s[8:9] offset:528
	s_add_u32 s8, s8, 0x10000
	s_addc_u32 s9, s9, 0
	v_pk_mul_f32 v[236:237], v[44:45], v[198:199] op_sel:[0,1] op_sel_hi:[1,1]
	v_pk_mul_f32 v[202:203], v[146:147], v[236:237]
	v_pk_mul_f32 v[236:237], v[46:47], v[198:199] op_sel:[0,1] op_sel_hi:[1,1]
	v_pk_mul_f32 v[204:205], v[148:149], v[236:237]
	global_store_dwordx4 v211, v[202:205], s[8:9] offset:0
	v_pk_mul_f32 v[236:237], v[40:41], v[198:199] op_sel:[0,1] op_sel_hi:[1,1]
	v_pk_mul_f32 v[206:207], v[150:151], v[236:237]
	v_pk_mul_f32 v[236:237], v[42:43], v[198:199] op_sel:[0,1] op_sel_hi:[1,1]
	v_pk_mul_f32 v[208:209], v[152:153], v[236:237]
	global_store_dwordx4 v211, v[206:209], s[8:9] offset:16
	v_pk_mul_f32 v[236:237], v[36:37], v[198:199] op_sel:[0,1] op_sel_hi:[1,1]
	v_pk_mul_f32 v[202:203], v[154:155], v[236:237]
	v_pk_mul_f32 v[236:237], v[38:39], v[198:199] op_sel:[0,1] op_sel_hi:[1,1]
	v_pk_mul_f32 v[204:205], v[156:157], v[236:237]
	global_store_dwordx4 v211, v[202:205], s[8:9] offset:512
	v_pk_mul_f32 v[236:237], v[32:33], v[198:199] op_sel:[0,1] op_sel_hi:[1,1]
	v_pk_mul_f32 v[206:207], v[158:159], v[236:237]
	v_pk_mul_f32 v[236:237], v[34:35], v[198:199] op_sel:[0,1] op_sel_hi:[1,1]
	v_pk_mul_f32 v[208:209], v[160:161], v[236:237]
	global_store_dwordx4 v211, v[206:209], s[8:9] offset:528
	s_add_u32 s8, s8, 0x10000
	s_addc_u32 s9, s9, 0
	v_pk_mul_f32 v[236:237], v[28:29], v[200:201] op_sel_hi:[1,0]
	v_pk_mul_f32 v[202:203], v[146:147], v[236:237]
	v_pk_mul_f32 v[236:237], v[30:31], v[200:201] op_sel_hi:[1,0]
	v_pk_mul_f32 v[204:205], v[148:149], v[236:237]
	global_store_dwordx4 v211, v[202:205], s[8:9] offset:0
	v_pk_mul_f32 v[236:237], v[24:25], v[200:201] op_sel_hi:[1,0]
	v_pk_mul_f32 v[206:207], v[150:151], v[236:237]
	v_pk_mul_f32 v[236:237], v[26:27], v[200:201] op_sel_hi:[1,0]
	v_pk_mul_f32 v[208:209], v[152:153], v[236:237]
	global_store_dwordx4 v211, v[206:209], s[8:9] offset:16
	v_pk_mul_f32 v[236:237], v[20:21], v[200:201] op_sel_hi:[1,0]
	v_pk_mul_f32 v[202:203], v[154:155], v[236:237]
	v_pk_mul_f32 v[236:237], v[22:23], v[200:201] op_sel_hi:[1,0]
	v_pk_mul_f32 v[204:205], v[156:157], v[236:237]
	global_store_dwordx4 v211, v[202:205], s[8:9] offset:512
	v_pk_mul_f32 v[236:237], v[16:17], v[200:201] op_sel_hi:[1,0]
	v_pk_mul_f32 v[206:207], v[158:159], v[236:237]
	v_pk_mul_f32 v[236:237], v[18:19], v[200:201] op_sel_hi:[1,0]
	v_pk_mul_f32 v[208:209], v[160:161], v[236:237]
	global_store_dwordx4 v211, v[206:209], s[8:9] offset:528
	s_add_u32 s8, s8, 0x10000
	s_addc_u32 s9, s9, 0
	v_pk_mul_f32 v[236:237], v[12:13], v[200:201] op_sel:[0,1] op_sel_hi:[1,1]
	v_pk_mul_f32 v[202:203], v[146:147], v[236:237]
	v_pk_mul_f32 v[236:237], v[14:15], v[200:201] op_sel:[0,1] op_sel_hi:[1,1]
	v_pk_mul_f32 v[204:205], v[148:149], v[236:237]
	global_store_dwordx4 v211, v[202:205], s[8:9] offset:0
	v_pk_mul_f32 v[236:237], v[4:5], v[200:201] op_sel:[0,1] op_sel_hi:[1,1]
	v_pk_mul_f32 v[206:207], v[150:151], v[236:237]
	v_pk_mul_f32 v[236:237], v[6:7], v[200:201] op_sel:[0,1] op_sel_hi:[1,1]
	v_pk_mul_f32 v[208:209], v[152:153], v[236:237]
	global_store_dwordx4 v211, v[206:209], s[8:9] offset:16
	v_pk_mul_f32 v[236:237], v[8:9], v[200:201] op_sel:[0,1] op_sel_hi:[1,1]
	v_pk_mul_f32 v[202:203], v[154:155], v[236:237]
	v_pk_mul_f32 v[236:237], v[10:11], v[200:201] op_sel:[0,1] op_sel_hi:[1,1]
	v_pk_mul_f32 v[204:205], v[156:157], v[236:237]
	global_store_dwordx4 v211, v[202:205], s[8:9] offset:512
	v_pk_mul_f32 v[236:237], v[0:1], v[200:201] op_sel:[0,1] op_sel_hi:[1,1]
	v_pk_mul_f32 v[206:207], v[158:159], v[236:237]
	v_pk_mul_f32 v[236:237], v[2:3], v[200:201] op_sel:[0,1] op_sel_hi:[1,1]
	v_pk_mul_f32 v[208:209], v[160:161], v[236:237]
	global_store_dwordx4 v211, v[206:209], s[8:9] offset:528
	v_mov_b32_e32 v239, 0x120000
	s_branch .LBB0_1145
